# bundle 4: attnA unit barrier removed, attnC back edge rotated, attnA touches the Q rows of passes 1-2 at unit start
# baseline (speedup 1.0000x reference)
; #define LAS __attribute__((address_space(3)))
; __device__ __forceinline__ int tidx() { int t = threadIdx.x; asm volatile("" : "+v"(t)); return t; }
; __device__ __forceinline__ void attnA_unit(const Args& a, int unit, LAS unsigned char* lds) {
;     const int tid = tidx(), wid = __builtin_amdgcn_readfirstlane(tid >> 6), lane = tid & 63, ql = lane & 31, h = lane >> 5;
;     const int b = unit / 24, rem = unit % 24, hh = rem >> 2, blk = rem & 3;
;     const bf16_t* P = (const bf16_t*)(a.ws + WS_P);
;     bf16_t* OA = (bf16_t*)(a.ws + OFF_OA); float* LSE = (float*)(a.ws + OFF_LSE); bf16_t* MIX = (bf16_t*)(a.ws + WS_MIX);
;     LAS unsigned char* wl = lds + wid * 8192;
;     const unsigned char* kbase = (const unsigned char*)(P + (size_t)b * SEQ * PW + 384 + 64 * hh);
;     const unsigned char* vbase = (const unsigned char*)(P + (size_t)b * SEQ * PW + 768 + 64 * hh);
; #pragma unroll 1
;     for (int pidx = 0; pidx < 3; ++pidx) {
;         const int dl = (pidx == 0) ? 1 : (pidx == 1 ? 4 : 16), Ls = SEQ / dl;
;         if (pidx == 2) { __syncthreads(); }
; #pragma unroll 1
;         for (int e = 0; e < 2; ++e) {
;             const int qt = 2 * wid + e, r = qt % dl, i0 = (512 * blk) / dl + 32 * (qt / dl);
;             const int tq = dl * (i0 + ql) + r;
;             bf16x8 qf[4];
;             { const bf16_t* qp = P + ((size_t)b * SEQ + tq) * PW + 64 * hh + 8 * h;
; #pragma unroll
;               for (int s = 0; s < 4; ++s) qf[s] = *(const bf16x8*)(qp + 16 * s); }
.LBB0_261:
	v_writelane_b32 v255, s0, 36
	s_lshl_b32 s0, s0, 5
	s_add_i32 s0, s0, s17
	s_mul_hi_i32 s2, s0, 0x2aaaaaab
	v_mov_b32_e32 v2, v225
	s_lshr_b32 s3, s2, 31
	s_ashr_i32 s2, s2, 2
	s_add_i32 s2, s2, s3
	v_readfirstlane_b32 s1, v2
	s_ashr_i32 s1, s1, 6
	s_mul_i32 s3, s2, 24
	s_sub_i32 s6, s0, s3
	s_lshl_b32 s3, s1, 14
	s_add_i32 s8, s3, 0
	s_ashr_i32 s3, s2, 31
	s_ashr_i32 s0, s6, 2
	s_lshl_b64 s[76:77], s[2:3], 11
	s_mul_hi_i32 s3, s2, 0xa00000
	s_mul_i32 s2, s2, 0xa00000
	s_add_u32 s4, s26, s2
	s_addc_u32 s5, s27, s3
	s_lshl_b32 s2, s0, 6
	s_ashr_i32 s3, s2, 31
	s_lshl_b64 s[2:3], s[2:3], 1
	s_add_u32 s4, s4, s2
	s_addc_u32 s5, s5, s3
	s_add_u32 s98, s4, 0x300
	s_addc_u32 s99, s5, 0
	v_writelane_b32 v255, s98, 38
	v_writelane_b32 v255, s99, 39
	s_lshl_b32 s83, s1, 1
	s_lshl_b32 s1, s6, 9
	s_and_b32 s1, s1, 0x600
	v_and_b32_e32 v3, 63, v2
	v_bfe_u32 v4, v2, 5, 1
	s_add_u32 s6, s26, s2
	s_addc_u32 s7, s27, s3
	v_lshlrev_b32_e32 v0, 4, v4
	v_mov_b32_e32 v1, v155
	v_lshlrev_b32_e32 v5, 4, v3
	s_waitcnt vmcnt(17)
	v_lshl_add_u64 v[112:113], s[6:7], 0, v[0:1]
	v_bfe_u32 v125, v2, 3, 3
	v_and_b32_e32 v147, 7, v3
	v_bfe_u32 v146, v3, 4, 2
	v_xor_b32_e32 v146, v146, v147
	v_lshlrev_b32_e32 v146, 4, v146
	v_lshlrev_b32_e32 v147, 4, v147
	v_and_b32_e32 v0, 0x70, v5
	v_lshl_add_u64 v[114:115], s[4:5], 0, v[0:1]
	v_or_b32_e32 v1, 8, v125
	v_or_b32_e32 v6, 24, v125
	v_lshrrev_b32_e32 v9, 1, v1
	v_lshrrev_b32_e32 v10, 1, v6
	v_and_b32_e32 v124, 31, v2
	v_xor_b32_e32 v9, v9, v2
	v_xor_b32_e32 v10, v10, v2
	v_lshrrev_b32_e32 v11, 1, v2
	v_bfe_u32 v12, v2, 1, 3
	v_lshlrev_b32_e32 v13, 7, v2
	v_lshrrev_b32_e32 v16, 2, v2
	v_and_b32_e32 v17, 16, v2
	v_lshlrev_b32_e32 v2, 2, v2
	v_writelane_b32 v255, s1, 37
	s_movk_i32 s1, 0x70
	v_and_b32_e32 v18, 4, v125
	v_and_or_b32 v2, v2, 12, v17
	v_bitop3_b32 v8, v5, s1, v3 bitop3:0x48
	v_and_b32_e32 v5, 0x380, v5
	v_and_b32_e32 v13, 0xf80, v13
	v_and_or_b32 v16, v16, 3, v18
	v_lshlrev_b32_e32 v17, 1, v2
	v_or_b32_e32 v2, 1, v18
	v_lshl_add_u32 v7, v125, 7, s8
	v_lshl_add_u32 v1, v1, 7, s8
	v_lshl_add_u32 v6, v6, 7, s8
	v_add_u32_e32 v5, s8, v5
	v_add_u32_e32 v13, s8, v13
	v_lshl_add_u32 v16, v16, 7, s8
	v_cmp_ge_u32_e64 s[8:9], v2, v124
	v_or_b32_e32 v2, 2, v18
	v_cmp_ge_u32_e64 s[12:13], v2, v124
	v_cmp_le_u32_e64 s[14:15], v2, v124
	v_or_b32_e32 v2, 3, v125
	v_cmp_ge_u32_e64 s[16:17], v2, v124
	v_cmp_le_u32_e64 s[18:19], v2, v124
	v_or_b32_e32 v2, 8, v18
	v_cmp_ge_u32_e64 s[20:21], v2, v124
	v_cmp_le_u32_e64 s[22:23], v2, v124
	v_or_b32_e32 v2, 9, v18
	v_cmp_ge_u32_e64 s[24:25], v2, v124
	v_cmp_le_u32_e64 s[26:27], v2, v124
	v_or_b32_e32 v2, 10, v18
	v_cmp_ge_u32_e64 s[28:29], v2, v124
	v_cmp_le_u32_e64 s[30:31], v2, v124
	v_or_b32_e32 v2, 11, v125
	v_cmp_ge_u32_e64 s[34:35], v2, v124
	v_cmp_le_u32_e64 s[36:37], v2, v124
	v_or_b32_e32 v2, 16, v18
	v_cmp_ge_u32_e64 s[38:39], v2, v124
	v_cmp_le_u32_e64 s[40:41], v2, v124
	v_or_b32_e32 v2, 17, v18
	v_cmp_ge_u32_e64 s[42:43], v2, v124
	v_cmp_le_u32_e64 s[44:45], v2, v124
	v_or_b32_e32 v2, 18, v18
	v_readlane_b32 s1, v255, 27
	v_cmp_ge_u32_e64 s[46:47], v2, v124
	v_cmp_le_u32_e64 s[48:49], v2, v124
	v_or_b32_e32 v2, 19, v125
	s_add_u32 s94, s1, s2
	v_readlane_b32 s1, v255, 28
	v_cmp_ge_u32_e64 s[50:51], v2, v124
	v_cmp_le_u32_e64 s[52:53], v2, v124
	v_or_b32_e32 v2, 24, v18
	s_addc_u32 s95, s1, s3
	v_readlane_b32 s1, v255, 31
	v_cmp_ge_u32_e64 s[54:55], v2, v124
	v_cmp_le_u32_e64 s[56:57], v2, v124
	v_or_b32_e32 v2, 25, v18
	s_add_u32 s2, s1, s2
	v_readlane_b32 s1, v255, 32
	v_cmp_ge_u32_e64 s[58:59], v2, v124
	v_cmp_le_u32_e64 s[60:61], v2, v124
	v_or_b32_e32 v2, 26, v18
	s_addc_u32 s3, s1, s3
	s_ashr_i32 s1, s0, 31
	v_lshlrev_b32_e32 v9, 4, v9
	v_lshlrev_b32_e32 v10, 4, v10
	v_bitop3_b32 v11, v4, v11, 7 bitop3:0x78
	v_bitop3_b32 v14, v4, v12, 2 bitop3:0x36
	v_bitop3_b32 v15, v4, v12, 4 bitop3:0x36
	v_bitop3_b32 v12, v4, v12, 6 bitop3:0x36
	v_cmp_ge_u32_e64 s[62:63], v2, v124
	v_cmp_le_u32_e64 s[64:65], v2, v124
	v_or_b32_e32 v2, 27, v125
	s_lshl_b64 s[0:1], s[0:1], 2
	v_readlane_b32 s33, v255, 29
	v_lshlrev_b32_e32 v154, 3, v4
	v_and_b32_e32 v9, 0x70, v9
	v_and_b32_e32 v10, 0x70, v10
	v_lshlrev_b32_e32 v11, 4, v11
	v_lshlrev_b32_e32 v14, 4, v14
	v_lshlrev_b32_e32 v15, 4, v15
	v_lshlrev_b32_e32 v12, 4, v12
	v_cmp_ge_u32_e64 s[66:67], v2, v124
	v_cmp_le_u32_e64 s[68:69], v2, v124
	v_lshlrev_b32_e32 v2, 2, v4
	s_add_u32 s88, s33, s0
	v_readlane_b32 s0, v255, 30
	v_cmp_ge_u32_e64 s[4:5], v18, v124
	v_cmp_le_u32_e64 s[6:7], v18, v124
	v_cmp_lt_u32_e64 s[10:11], v18, v124
	s_waitcnt vmcnt(16)
	v_lshl_add_u64 v[116:117], s[94:95], 0, v[154:155]
	s_addc_u32 s89, s0, s1
	v_cmp_gt_u32_e64 s[70:71], 32, v3
	v_lshl_add_u64 v[118:119], s[2:3], 0, v[154:155]
	v_add_u32_e32 v126, v7, v8
	v_add_u32_e32 v127, v1, v9
	v_add_u32_e32 v128, v6, v10
	v_add_u32_e32 v129, v5, v0
	v_add_u32_e32 v130, v13, v11
	v_add_u32_e32 v131, v13, v14
	v_add_u32_e32 v132, v13, v15
	v_add_u32_e32 v133, v13, v12
	v_add_u32_e32 v134, v16, v17
	v_lshlrev_b32_e32 v154, 1, v2
	v_and_b32_e32 v192, 7, v124
	v_lshlrev_b32_e32 v192, 4, v192
	v_lshl_or_b32 v192, v124, 7, v192
	v_or_b32_e32 v192, v192, v154
	v_lshlrev_b32_e32 v194, 4, v125
	v_xor_b32_e32 v194, v194, v147
	v_lshl_add_u32 v193, v125, 7, v194
	v_readlane_b32 s1, v255, 37
	v_bfe_u32 v129, v225, 5, 1
	v_or_b32_e32 v129, s83, v129
	v_and_b32_e32 v136, 3, v129
	s_lshr_b32 s0, s1, 2
	v_lshrrev_b32_e32 v128, 2, v129
	v_lshlrev_b32_e32 v128, 5, v128
	v_add_u32_e32 v128, s0, v128
	v_add_u32_e32 v128, v128, v124
	v_lshlrev_b32_e32 v128, 2, v128
	v_add3_u32 v128, v128, v136, s76
	s_movk_i32 s0, 0x1400
	v_mad_u64_u32 v[126:127], s[98:99], v128, s0, v[112:113]
	global_load_dword v158, v[126:127], off
	v_and_b32_e32 v136, 15, v129
	s_lshr_b32 s0, s1, 4
	v_lshrrev_b32_e32 v128, 4, v129
	v_lshlrev_b32_e32 v128, 5, v128
	v_add_u32_e32 v128, s0, v128
	v_add_u32_e32 v128, v128, v124
	v_lshlrev_b32_e32 v128, 4, v128
	v_add3_u32 v128, v128, v136, s76
	s_movk_i32 s0, 0x1400
	v_mad_u64_u32 v[126:127], s[98:99], v128, s0, v[112:113]
	global_load_dword v159, v[126:127], off
	s_mov_b32 s82, 0
	s_branch .LBB0_263
